# loop-edge (7.11): SwiGLU K-loop scalar bookkeeping and LDS address adds moved out of the 16-read load segment heads (persistent base VGPRs, updates in read shadow)
# baseline (speedup 1.0000x reference)
.LBB0_621:
	v_ashrrev_i32_e32 v2, 31, v0
	v_lshrrev_b32_e32 v2, 26, v2
	v_lshlrev_b32_e32 v1, 4, v0
	v_add_u32_e32 v2, v0, v2
	v_bfe_i32 v0, v0, 27, 1
	v_lshrrev_b32_e32 v0, 22, v0
	v_add_u32_e32 v0, v1, v0
	v_and_b32_e32 v0, 0xfffffc00, v0
	v_sub_u32_e32 v0, v1, v0
	v_ashrrev_i32_e32 v9, 6, v2
	v_lshrrev_b32_e32 v2, 4, v0
	v_bitop3_b32 v0, v2, v0, 32 bitop3:0x6c
	v_ashrrev_i32_e32 v3, 31, v0
	v_lshrrev_b32_e32 v3, 26, v3
	v_add_u32_e32 v3, v0, v3
	v_lshlrev_b32_e32 v2, 3, v9
	v_ashrrev_i32_e32 v10, 6, v3
	v_and_b32_e32 v3, 0xc0, v3
	v_and_b32_e32 v2, -16, v2
	v_sub_u32_e32 v0, v0, v3
	v_add_u32_e32 v2, v10, v2
	v_ashrrev_i16_sdwa v0, v196, sext(v0) dst_sel:DWORD dst_unused:UNUSED_PAD src0_sel:DWORD src1_sel:BYTE_0
	v_lshlrev_b32_e32 v4, 5, v9
	v_bfe_i32 v11, v0, 0, 16
	v_lshlrev_b32_e32 v0, 1, v2
	v_lshrrev_b32_e32 v3, 2, v2
	v_and_b32_e32 v5, 3, v10
	s_mov_b32 s0, 0x1fffe0
	v_and_b32_e32 v4, 32, v4
	v_and_b32_e32 v0, 24, v0
	v_and_b32_e32 v3, 4, v3
	v_and_or_b32 v5, v2, s0, v5
	v_or3_b32 v0, v5, v3, v0
	v_add_lshl_u32 v3, v4, v11, 1
	s_nop 0
	v_add_u32_e32 v0, 0x2000, v1
	v_ashrrev_i32_e32 v1, 31, v0
	v_lshrrev_b32_e32 v1, 22, v1
	v_add_u32_e32 v1, v0, v1
	v_ashrrev_i32_e32 v12, 10, v1
	v_mul_i32_i24_e32 v1, 0x400, v12
	v_sub_u32_e32 v0, v0, v1
	v_lshrrev_b32_e32 v1, 4, v0
	v_bitop3_b32 v0, v1, v0, 32 bitop3:0x6c
	s_nop 0
	v_ashrrev_i32_e32 v2, 31, v0
	v_lshrrev_b32_e32 v2, 26, v2
	v_lshlrev_b32_e32 v1, 3, v12
	v_add_u32_e32 v2, v0, v2
	v_and_b32_e32 v1, -16, v1
	v_ashrrev_i32_e32 v13, 6, v2
	s_ashr_i32 s6, s4, 6
	s_ashr_i32 s5, s4, 8
	v_add_u32_e32 v1, v13, v1
	v_and_b32_e32 v4, 3, v13
	s_lshl_b32 s48, s6, 10
	v_and_or_b32 v4, v1, s0, v4
	s_and_b64 s[0:1], s[2:3], exec
	s_cselect_b32 s0, 0, 0x1380000
	s_add_u32 s49, s51, s0
	v_readlane_b32 s0, v241, 60
	v_and_b32_e32 v2, 0xc0, v2
	s_addc_u32 s50, s0, 0
	s_ashr_i32 s29, s28, 31
	s_ashr_i32 s17, s16, 31
	v_sub_u32_e32 v0, v0, v2
	s_lshl_b64 s[0:1], s[28:29], 19
	s_lshl_b64 s[2:3], s[16:17], 19
	v_ashrrev_i16_sdwa v0, v196, sext(v0) dst_sel:DWORD dst_unused:UNUSED_PAD src0_sel:DWORD src1_sel:BYTE_0
	s_add_u32 s40, s49, s2
	v_lshlrev_b32_e32 v3, 5, v12
	v_bfe_i32 v14, v0, 0, 16
	v_lshlrev_b32_e32 v0, 1, v1
	v_lshrrev_b32_e32 v2, 2, v1
	s_addc_u32 s41, s50, s3
	s_add_i32 s51, s48, 0
	v_and_b32_e32 v3, 32, v3
	v_and_b32_e32 v0, 24, v0
	v_and_b32_e32 v2, 4, v2
	s_lshr_b32 s86, s4, 6
	s_and_b32 s87, s86, 1
	s_lshl_b32 s87, s87, 2
	v_lshrrev_b32_e32 v243, 4, v8
	v_or_b32_e32 v243, s87, v243
	v_and_b32_e32 v244, 7, v8
	v_xor_b32_e32 v243, v244, v243
	v_lshlrev_b32_e32 v243, 4, v243
	v_lshrrev_b32_e32 v244, 3, v8
	s_lshl_b32 s86, s86, 3
	v_add_u32_e32 v244, s86, v244
	v_lshl_add_u32 v132, v244, 11, v243
	v_add_u32_e32 v136, 0x20000, v132
	v_and_b32_e32 v245, 31, v244
	v_bfe_u32 v246, v245, 2, 2
	v_lshlrev_b32_e32 v246, 3, v246
	v_bfe_u32 v247, v245, 4, 1
	v_lshl_or_b32 v246, v247, 2, v246
	v_and_b32_e32 v247, 3, v245
	v_or_b32_e32 v246, v246, v247
	v_and_b32_e32 v247, 0xffffffe0, v244
	v_or_b32_e32 v246, v247, v246
	v_lshl_add_u32 v134, v246, 11, v243
	v_add_u32_e32 v138, 0x20000, v134
	v_and_b32_e32 v245, 15, v8
	v_lshrrev_b32_e32 v246, 4, v8
	v_lshrrev_b32_e32 v247, 1, v245
	v_xor_b32_e32 v246, v246, v247
	v_lshlrev_b32_e32 v246, 4, v246
	v_lshl_or_b32 v246, v245, 7, v246
	s_lshr_b32 s86, s4, 8
	s_lshl_b32 s86, s86, 13
	v_or_b32_e32 v173, s86, v246
	v_xor_b32_e32 v244, 64, v173
	s_lshr_b32 s86, s4, 6
	s_and_b32 s86, s86, 3
	s_lshl_b32 s86, s86, 12
	v_or_b32_e32 v172, s86, v246
	v_xor_b32_e32 v243, 64, v172
	v_add_u32_e32 v248, 0x10000, v172
	v_add_u32_e32 v249, 0x10000, v243
	v_add_u32_e32 v250, 0x14000, v172
	v_add_u32_e32 v251, 0x14000, v243
	s_add_i32 m0, s51, 0x10000
	v_or3_b32 v0, v4, v2, v0
	v_add_lshl_u32 v2, v3, v14, 1
	global_load_lds_dwordx4 v134, s[40:41]
	s_add_i32 m0, s51, 0x12000
	s_nop 0
	s_add_u32 s2, s40, 0x40000
	global_load_lds_dwordx4 v138, s[40:41]
	s_addc_u32 s3, s41, 0
	s_add_i32 m0, s51, 0x14000
	s_nop 0
	global_load_lds_dwordx4 v134, s[2:3]
	s_add_i32 m0, s51, 0x16000
	s_add_u32 s34, s30, s0
	s_addc_u32 s35, s31, s1
	s_add_i32 s60, s51, 0x2000
	global_load_lds_dwordx4 v138, s[2:3]
	s_mov_b32 m0, s51
	s_add_u32 s0, s34, 0x40000
	global_load_lds_dwordx4 v132, s[34:35]
	s_mov_b32 m0, s60
	s_addc_u32 s1, s35, 0
	s_add_i32 s61, s51, 0x4000
	global_load_lds_dwordx4 v136, s[34:35]
	s_mov_b32 m0, s61
	s_add_i32 s64, s51, 0x6000
	global_load_lds_dwordx4 v132, s[0:1]
	s_mov_b32 m0, s64
	v_mov_b32_e32 v135, v159
	global_load_lds_dwordx4 v136, s[0:1]
	v_mov_b32_e32 v139, v159
	v_mov_b32_e32 v133, v159
	v_mov_b32_e32 v137, v159
	s_cmp_eq_u32 s5, 1
	v_lshl_add_u64 v[6:7], s[40:41], 0, v[134:135]
	v_lshl_add_u64 v[4:5], s[40:41], 0, v[138:139]
	v_lshl_add_u64 v[0:1], s[34:35], 0, v[132:133]
	s_cselect_b64 s[0:1], -1, 0
	v_lshl_add_u64 v[2:3], s[34:35], 0, v[136:137]
	s_add_i32 m0, s51, 0x18000
	v_lshl_add_u64 v[6:7], v[6:7], 0, s[14:15]
	global_load_lds_dwordx4 v[6:7], off
	v_lshl_add_u64 v[4:5], v[4:5], 0, s[14:15]
	s_add_i32 m0, s51, 0x1a000
	s_add_i32 s76, s51, 0x8000
	s_add_i32 s77, s51, 0xa000
	global_load_lds_dwordx4 v[4:5], off
	v_lshl_add_u64 v[0:1], v[0:1], 0, s[14:15]
	s_mov_b32 m0, s76
	s_add_u32 s2, s40, 0x40080
	global_load_lds_dwordx4 v[0:1], off
	v_lshl_add_u64 v[0:1], v[2:3], 0, s[14:15]
	s_mov_b32 m0, s77
	s_addc_u32 s3, s41, 0
	global_load_lds_dwordx4 v[0:1], off
	s_add_i32 m0, s51, 0x1c000
	v_lshl_add_u64 v[0:1], s[2:3], 0, v[134:135]
	global_load_lds_dwordx4 v[0:1], off
	v_lshl_add_u64 v[0:1], s[2:3], 0, v[138:139]
	s_add_i32 m0, s51, 0x1e000
	s_nop 0
	global_load_lds_dwordx4 v[0:1], off
	s_cmp_lg_u32 s5, 1
	s_cbranch_scc1 .LBB0_623
	s_barrier

.LBB0_628:
	s_ashr_i32 s13, s12, 31
	s_lshl_b64 s[6:7], s[12:13], 19
	s_add_u32 s6, s30, s6
	s_addc_u32 s7, s31, s7
	s_and_b64 s[24:25], s[38:39], exec
	s_cselect_b32 s13, s7, s35
	s_cselect_b32 s29, s6, s34
	s_ashr_i32 s5, s4, 31
	s_lshl_b64 s[24:25], s[4:5], 19
	s_add_u32 s24, s49, s24
	s_addc_u32 s25, s50, s25
	s_and_b64 s[42:43], s[38:39], exec
	s_cselect_b32 s5, s25, s41
	s_cselect_b32 s82, s24, s40
	s_add_u32 s34, s34, 0x40080
	s_addc_u32 s35, s35, 0
	s_add_u32 s83, s40, 0x100
	s_addc_u32 s84, s41, 0
	s_mov_b32 s85, -2
	s_add_u32 s86, s34, 0xfffc0000
	s_addc_u32 s87, s35, -1
	s_mov_b32 m0, s76
	ds_read_b128 v[128:131], v248
	global_load_lds_dwordx4 v132, s[86:87]
	s_mov_b32 m0, s77
	ds_read_b128 v[144:147], v249
	global_load_lds_dwordx4 v136, s[86:87]
	ds_read_b128 v[148:151], v248 offset:2048
	ds_read_b128 v[152:155], v249 offset:2048
	ds_read_b128 v[174:177], v250
	ds_read_b128 v[178:181], v251
	ds_read_b128 v[182:185], v250 offset:2048
	ds_read_b128 v[186:189], v251 offset:2048
	ds_read_b128 v[190:193], v173
	ds_read_b128 v[198:201], v244
	ds_read_b128 v[202:205], v173 offset:2048
	ds_read_b128 v[206:209], v244 offset:2048
	ds_read_b128 v[210:213], v173 offset:4096
	ds_read_b128 v[214:217], v244 offset:4096
	ds_read_b128 v[218:221], v173 offset:6144
	ds_read_b128 v[222:225], v244 offset:6144
	s_add_u32 s40, s34, 0xfffc0080
	s_addc_u32 s41, s35, -1
	s_cmp_eq_u32 s85, 12
	s_cselect_b32 s43, s13, s41
	s_cselect_b32 s42, s29, s40
	s_cselect_b32 s41, s5, s84
	s_cselect_b32 s40, s82, s83
	s_waitcnt vmcnt(6)
	s_waitcnt lgkmcnt(0)
	s_barrier
	s_setprio 1
	v_mfma_f32_16x16x32_bf16 v[124:127], v[128:131], v[190:193], 0
	v_mfma_f32_16x16x32_bf16 v[116:119], v[148:151], v[190:193], 0
	v_mfma_f32_16x16x32_bf16 v[108:111], v[128:131], v[202:205], 0
	s_add_i32 m0, s51, 0xc000
	v_mfma_f32_16x16x32_bf16 v[100:103], v[148:151], v[202:205], 0
	v_mfma_f32_16x16x32_bf16 v[92:95], v[128:131], v[210:213], 0
	global_load_lds_dwordx4 v132, s[34:35]
	v_mfma_f32_16x16x32_bf16 v[84:87], v[148:151], v[210:213], 0
	v_mfma_f32_16x16x32_bf16 v[76:79], v[128:131], v[218:221], 0
	v_mfma_f32_16x16x32_bf16 v[68:71], v[148:151], v[218:221], 0
	v_mfma_f32_16x16x32_bf16 v[124:127], v[144:147], v[198:201], v[124:127]
	v_mfma_f32_16x16x32_bf16 v[116:119], v[152:155], v[198:201], v[116:119]
	v_mfma_f32_16x16x32_bf16 v[108:111], v[144:147], v[206:209], v[108:111]
	s_add_i32 m0, s51, 0xe000
	v_mfma_f32_16x16x32_bf16 v[100:103], v[152:155], v[206:209], v[100:103]
	v_mfma_f32_16x16x32_bf16 v[92:95], v[144:147], v[214:217], v[92:95]
	global_load_lds_dwordx4 v136, s[34:35]
	v_mfma_f32_16x16x32_bf16 v[84:87], v[152:155], v[214:217], v[84:87]
	v_mfma_f32_16x16x32_bf16 v[76:79], v[144:147], v[222:225], v[76:79]
	v_mfma_f32_16x16x32_bf16 v[68:71], v[152:155], v[222:225], v[68:71]
	s_setprio 0
	s_setprio 1
	v_mfma_f32_16x16x32_bf16 v[120:123], v[174:177], v[190:193], 0
	v_mfma_f32_16x16x32_bf16 v[112:115], v[182:185], v[190:193], 0
	v_mfma_f32_16x16x32_bf16 v[104:107], v[174:177], v[202:205], 0
	v_mfma_f32_16x16x32_bf16 v[96:99], v[182:185], v[202:205], 0
	v_mfma_f32_16x16x32_bf16 v[88:91], v[174:177], v[210:213], 0
	v_mfma_f32_16x16x32_bf16 v[80:83], v[182:185], v[210:213], 0
	v_mfma_f32_16x16x32_bf16 v[72:75], v[174:177], v[218:221], 0
	v_mfma_f32_16x16x32_bf16 v[64:67], v[182:185], v[218:221], 0
	v_mfma_f32_16x16x32_bf16 v[120:123], v[178:181], v[198:201], v[120:123]
	v_mfma_f32_16x16x32_bf16 v[112:115], v[186:189], v[198:201], v[112:115]
	v_mfma_f32_16x16x32_bf16 v[104:107], v[178:181], v[206:209], v[104:107]
	v_mfma_f32_16x16x32_bf16 v[96:99], v[186:189], v[206:209], v[96:99]
	v_mfma_f32_16x16x32_bf16 v[88:91], v[178:181], v[214:217], v[88:91]
	v_mfma_f32_16x16x32_bf16 v[80:83], v[186:189], v[214:217], v[80:83]
	v_mfma_f32_16x16x32_bf16 v[72:75], v[178:181], v[222:225], v[72:75]
	v_mfma_f32_16x16x32_bf16 v[64:67], v[186:189], v[222:225], v[64:67]
	s_setprio 0
	s_barrier
	s_add_i32 s62, s48, 0x10000
	s_mov_b32 m0, s62
	ds_read_b128 v[190:193], v173 offset:16384
	global_load_lds_dwordx4 v134, s[40:41]
	s_add_i32 m0, s62, 0x2000
	ds_read_b128 v[198:201], v244 offset:16384
	global_load_lds_dwordx4 v138, s[40:41]
	ds_read_b128 v[202:205], v173 offset:18432
	ds_read_b128 v[206:209], v244 offset:18432
	ds_read_b128 v[210:213], v173 offset:20480
	ds_read_b128 v[214:217], v244 offset:20480
	ds_read_b128 v[218:221], v173 offset:22528
	ds_read_b128 v[222:225], v244 offset:22528
	s_add_u32 s86, s40, 0x40000
	s_addc_u32 s87, s41, 0
	s_add_i32 s62, s48, 0x14000
	s_waitcnt vmcnt(4)
	s_waitcnt lgkmcnt(0)
	s_barrier
	s_setprio 1
	v_mfma_f32_16x16x32_bf16 v[60:63], v[128:131], v[190:193], 0
	v_mfma_f32_16x16x32_bf16 v[52:55], v[148:151], v[190:193], 0
	v_mfma_f32_16x16x32_bf16 v[44:47], v[128:131], v[202:205], 0
	s_mov_b32 m0, s62
	v_mfma_f32_16x16x32_bf16 v[36:39], v[148:151], v[202:205], 0
	v_mfma_f32_16x16x32_bf16 v[28:31], v[128:131], v[210:213], 0
	global_load_lds_dwordx4 v134, s[86:87]
	v_mfma_f32_16x16x32_bf16 v[20:23], v[148:151], v[210:213], 0
	v_mfma_f32_16x16x32_bf16 v[8:11], v[128:131], v[218:221], 0
	v_mfma_f32_16x16x32_bf16 v[4:7], v[148:151], v[218:221], 0
	v_mfma_f32_16x16x32_bf16 v[60:63], v[144:147], v[198:201], v[60:63]
	v_mfma_f32_16x16x32_bf16 v[52:55], v[152:155], v[198:201], v[52:55]
	v_mfma_f32_16x16x32_bf16 v[44:47], v[144:147], v[206:209], v[44:47]
	s_add_i32 m0, s62, 0x2000
	v_mfma_f32_16x16x32_bf16 v[36:39], v[152:155], v[206:209], v[36:39]
	v_mfma_f32_16x16x32_bf16 v[28:31], v[144:147], v[214:217], v[28:31]
	global_load_lds_dwordx4 v138, s[86:87]
	v_mfma_f32_16x16x32_bf16 v[20:23], v[152:155], v[214:217], v[20:23]
	v_mfma_f32_16x16x32_bf16 v[8:11], v[144:147], v[222:225], v[8:11]
	v_mfma_f32_16x16x32_bf16 v[4:7], v[152:155], v[222:225], v[4:7]
	s_setprio 0
	s_setprio 1
	v_mfma_f32_16x16x32_bf16 v[56:59], v[174:177], v[190:193], 0
	v_mfma_f32_16x16x32_bf16 v[48:51], v[182:185], v[190:193], 0
	v_mfma_f32_16x16x32_bf16 v[40:43], v[174:177], v[202:205], 0
	v_mfma_f32_16x16x32_bf16 v[32:35], v[182:185], v[202:205], 0
	v_mfma_f32_16x16x32_bf16 v[24:27], v[174:177], v[210:213], 0
	v_mfma_f32_16x16x32_bf16 v[16:19], v[182:185], v[210:213], 0
	v_mfma_f32_16x16x32_bf16 v[12:15], v[174:177], v[218:221], 0
	v_mfma_f32_16x16x32_bf16 v[0:3], v[182:185], v[218:221], 0
	v_mfma_f32_16x16x32_bf16 v[56:59], v[178:181], v[198:201], v[56:59]
	v_mfma_f32_16x16x32_bf16 v[48:51], v[186:189], v[198:201], v[48:51]
	v_mfma_f32_16x16x32_bf16 v[40:43], v[178:181], v[206:209], v[40:43]
	v_mfma_f32_16x16x32_bf16 v[32:35], v[186:189], v[206:209], v[32:35]
	v_mfma_f32_16x16x32_bf16 v[24:27], v[178:181], v[214:217], v[24:27]
	v_mfma_f32_16x16x32_bf16 v[16:19], v[186:189], v[214:217], v[16:19]
	v_mfma_f32_16x16x32_bf16 v[12:15], v[178:181], v[222:225], v[12:15]
	v_mfma_f32_16x16x32_bf16 v[0:3], v[186:189], v[222:225], v[0:3]
	s_setprio 0
	s_barrier
	s_mov_b32 m0, s51
	ds_read_b128 v[128:131], v248 offset:32768
	global_load_lds_dwordx4 v132, s[42:43]
	s_mov_b32 m0, s60
	ds_read_b128 v[144:147], v249 offset:32768
	global_load_lds_dwordx4 v136, s[42:43]
	ds_read_b128 v[148:151], v248 offset:34816
	ds_read_b128 v[152:155], v249 offset:34816
	ds_read_b128 v[174:177], v250 offset:32768
	ds_read_b128 v[178:181], v251 offset:32768
	ds_read_b128 v[182:185], v250 offset:34816
	ds_read_b128 v[186:189], v251 offset:34816
	ds_read_b128 v[190:193], v173 offset:32768
	ds_read_b128 v[198:201], v244 offset:32768
	ds_read_b128 v[202:205], v173 offset:34816
	ds_read_b128 v[206:209], v244 offset:34816
	ds_read_b128 v[210:213], v173 offset:36864
	ds_read_b128 v[214:217], v244 offset:36864
	ds_read_b128 v[218:221], v173 offset:38912
	ds_read_b128 v[222:225], v244 offset:38912
	s_add_u32 s42, s42, 0x40000
	s_addc_u32 s43, s43, 0
	s_waitcnt vmcnt(6)
	s_waitcnt lgkmcnt(0)
	s_barrier
	s_setprio 1
	v_mfma_f32_16x16x32_bf16 v[124:127], v[128:131], v[190:193], v[124:127]
	v_mfma_f32_16x16x32_bf16 v[116:119], v[148:151], v[190:193], v[116:119]
	v_mfma_f32_16x16x32_bf16 v[108:111], v[128:131], v[202:205], v[108:111]
	s_mov_b32 m0, s61
	v_mfma_f32_16x16x32_bf16 v[100:103], v[148:151], v[202:205], v[100:103]
	v_mfma_f32_16x16x32_bf16 v[92:95], v[128:131], v[210:213], v[92:95]
	global_load_lds_dwordx4 v132, s[42:43]
	v_mfma_f32_16x16x32_bf16 v[84:87], v[148:151], v[210:213], v[84:87]
	v_mfma_f32_16x16x32_bf16 v[76:79], v[128:131], v[218:221], v[76:79]
	v_mfma_f32_16x16x32_bf16 v[68:71], v[148:151], v[218:221], v[68:71]
	v_mfma_f32_16x16x32_bf16 v[124:127], v[144:147], v[198:201], v[124:127]
	v_mfma_f32_16x16x32_bf16 v[116:119], v[152:155], v[198:201], v[116:119]
	v_mfma_f32_16x16x32_bf16 v[108:111], v[144:147], v[206:209], v[108:111]
	s_mov_b32 m0, s64
	v_mfma_f32_16x16x32_bf16 v[100:103], v[152:155], v[206:209], v[100:103]
	v_mfma_f32_16x16x32_bf16 v[92:95], v[144:147], v[214:217], v[92:95]
	global_load_lds_dwordx4 v136, s[42:43]
	v_mfma_f32_16x16x32_bf16 v[84:87], v[152:155], v[214:217], v[84:87]
	v_mfma_f32_16x16x32_bf16 v[76:79], v[144:147], v[222:225], v[76:79]
	v_mfma_f32_16x16x32_bf16 v[68:71], v[152:155], v[222:225], v[68:71]
	s_setprio 0
	s_setprio 1
	v_mfma_f32_16x16x32_bf16 v[120:123], v[174:177], v[190:193], v[120:123]
	v_mfma_f32_16x16x32_bf16 v[112:115], v[182:185], v[190:193], v[112:115]
	v_mfma_f32_16x16x32_bf16 v[104:107], v[174:177], v[202:205], v[104:107]
	v_mfma_f32_16x16x32_bf16 v[96:99], v[182:185], v[202:205], v[96:99]
	v_mfma_f32_16x16x32_bf16 v[88:91], v[174:177], v[210:213], v[88:91]
	v_mfma_f32_16x16x32_bf16 v[80:83], v[182:185], v[210:213], v[80:83]
	v_mfma_f32_16x16x32_bf16 v[72:75], v[174:177], v[218:221], v[72:75]
	v_mfma_f32_16x16x32_bf16 v[64:67], v[182:185], v[218:221], v[64:67]
	v_mfma_f32_16x16x32_bf16 v[120:123], v[178:181], v[198:201], v[120:123]
	v_mfma_f32_16x16x32_bf16 v[112:115], v[186:189], v[198:201], v[112:115]
	v_mfma_f32_16x16x32_bf16 v[104:107], v[178:181], v[206:209], v[104:107]
	v_mfma_f32_16x16x32_bf16 v[96:99], v[186:189], v[206:209], v[96:99]
	v_mfma_f32_16x16x32_bf16 v[88:91], v[178:181], v[214:217], v[88:91]
	v_mfma_f32_16x16x32_bf16 v[80:83], v[186:189], v[214:217], v[80:83]
	v_mfma_f32_16x16x32_bf16 v[72:75], v[178:181], v[222:225], v[72:75]
	v_mfma_f32_16x16x32_bf16 v[64:67], v[186:189], v[222:225], v[64:67]
	s_setprio 0
	s_barrier
	s_add_i32 s42, s48, 0x18000
	s_add_u32 s40, s40, 0x80
	s_addc_u32 s41, s41, 0
	s_mov_b32 m0, s42
	ds_read_b128 v[190:193], v173 offset:49152
	global_load_lds_dwordx4 v134, s[40:41]
	s_add_i32 m0, s42, 0x2000
	ds_read_b128 v[198:201], v244 offset:49152
	global_load_lds_dwordx4 v138, s[40:41]
	ds_read_b128 v[202:205], v173 offset:51200
	ds_read_b128 v[206:209], v244 offset:51200
	ds_read_b128 v[210:213], v173 offset:53248
	ds_read_b128 v[214:217], v244 offset:53248
	ds_read_b128 v[218:221], v173 offset:55296
	ds_read_b128 v[222:225], v244 offset:55296
	s_add_u32 s40, s40, 0x40000
	s_addc_u32 s41, s41, 0
	s_add_i32 s42, s48, 0x1c000
	s_add_i32 s85, s85, 2
	s_add_u32 s34, s34, 0x100
	s_addc_u32 s35, s35, 0
	s_add_u32 s83, s83, 0x100
	s_addc_u32 s84, s84, 0
	s_waitcnt vmcnt(4)
	s_waitcnt lgkmcnt(0)
	s_barrier
	s_setprio 1
	v_mfma_f32_16x16x32_bf16 v[60:63], v[128:131], v[190:193], v[60:63]
	v_mfma_f32_16x16x32_bf16 v[52:55], v[148:151], v[190:193], v[52:55]
	v_mfma_f32_16x16x32_bf16 v[44:47], v[128:131], v[202:205], v[44:47]
	s_mov_b32 m0, s42
	v_mfma_f32_16x16x32_bf16 v[36:39], v[148:151], v[202:205], v[36:39]
	v_mfma_f32_16x16x32_bf16 v[28:31], v[128:131], v[210:213], v[28:31]
	global_load_lds_dwordx4 v134, s[40:41]
	v_mfma_f32_16x16x32_bf16 v[20:23], v[148:151], v[210:213], v[20:23]
	v_mfma_f32_16x16x32_bf16 v[8:11], v[128:131], v[218:221], v[8:11]
	v_mfma_f32_16x16x32_bf16 v[4:7], v[148:151], v[218:221], v[4:7]
	v_mfma_f32_16x16x32_bf16 v[60:63], v[144:147], v[198:201], v[60:63]
	v_mfma_f32_16x16x32_bf16 v[52:55], v[152:155], v[198:201], v[52:55]
	v_mfma_f32_16x16x32_bf16 v[44:47], v[144:147], v[206:209], v[44:47]
	s_add_i32 m0, s42, 0x2000
	v_mfma_f32_16x16x32_bf16 v[36:39], v[152:155], v[206:209], v[36:39]
	v_mfma_f32_16x16x32_bf16 v[28:31], v[144:147], v[214:217], v[28:31]
	global_load_lds_dwordx4 v138, s[40:41]
	v_mfma_f32_16x16x32_bf16 v[20:23], v[152:155], v[214:217], v[20:23]
	v_mfma_f32_16x16x32_bf16 v[8:11], v[144:147], v[222:225], v[8:11]
	v_mfma_f32_16x16x32_bf16 v[4:7], v[152:155], v[222:225], v[4:7]
	s_setprio 0
	s_setprio 1
	v_mfma_f32_16x16x32_bf16 v[56:59], v[174:177], v[190:193], v[56:59]
	v_mfma_f32_16x16x32_bf16 v[48:51], v[182:185], v[190:193], v[48:51]
	v_mfma_f32_16x16x32_bf16 v[40:43], v[174:177], v[202:205], v[40:43]
	v_mfma_f32_16x16x32_bf16 v[32:35], v[182:185], v[202:205], v[32:35]
	v_mfma_f32_16x16x32_bf16 v[24:27], v[174:177], v[210:213], v[24:27]
	v_mfma_f32_16x16x32_bf16 v[16:19], v[182:185], v[210:213], v[16:19]
	v_mfma_f32_16x16x32_bf16 v[12:15], v[174:177], v[218:221], v[12:15]
	v_mfma_f32_16x16x32_bf16 v[0:3], v[182:185], v[218:221], v[0:3]
	v_mfma_f32_16x16x32_bf16 v[56:59], v[178:181], v[198:201], v[56:59]
	v_mfma_f32_16x16x32_bf16 v[48:51], v[186:189], v[198:201], v[48:51]
	v_mfma_f32_16x16x32_bf16 v[40:43], v[178:181], v[206:209], v[40:43]
	v_mfma_f32_16x16x32_bf16 v[32:35], v[186:189], v[206:209], v[32:35]
	v_mfma_f32_16x16x32_bf16 v[24:27], v[178:181], v[214:217], v[24:27]
	v_mfma_f32_16x16x32_bf16 v[16:19], v[186:189], v[214:217], v[16:19]
	v_mfma_f32_16x16x32_bf16 v[12:15], v[178:181], v[222:225], v[12:15]
	v_mfma_f32_16x16x32_bf16 v[0:3], v[186:189], v[222:225], v[0:3]
	s_setprio 0
	s_barrier
.LBB0_629:
	s_add_u32 s86, s34, 0xfffc0000
	s_addc_u32 s87, s35, -1
	s_mov_b32 m0, s76
	ds_read_b128 v[128:131], v248
	global_load_lds_dwordx4 v132, s[86:87]
	s_mov_b32 m0, s77
	ds_read_b128 v[144:147], v249
	global_load_lds_dwordx4 v136, s[86:87]
	ds_read_b128 v[148:151], v248 offset:2048
	ds_read_b128 v[152:155], v249 offset:2048
	ds_read_b128 v[174:177], v250
	ds_read_b128 v[178:181], v251
	ds_read_b128 v[182:185], v250 offset:2048
	ds_read_b128 v[186:189], v251 offset:2048
	ds_read_b128 v[190:193], v173
	ds_read_b128 v[198:201], v244
	ds_read_b128 v[202:205], v173 offset:2048
	ds_read_b128 v[206:209], v244 offset:2048
	ds_read_b128 v[210:213], v173 offset:4096
	ds_read_b128 v[214:217], v244 offset:4096
	ds_read_b128 v[218:221], v173 offset:6144
	ds_read_b128 v[222:225], v244 offset:6144
	s_add_u32 s40, s34, 0xfffc0080
	s_addc_u32 s41, s35, -1
	s_cmp_eq_u32 s85, 12
	s_cselect_b32 s43, s13, s41
	s_cselect_b32 s42, s29, s40
	s_cselect_b32 s41, s5, s84
	s_cselect_b32 s40, s82, s83
	s_waitcnt vmcnt(6)
	s_waitcnt lgkmcnt(0)
	s_barrier
	s_setprio 1
	v_mfma_f32_16x16x32_bf16 v[124:127], v[128:131], v[190:193], v[124:127]
	v_mfma_f32_16x16x32_bf16 v[116:119], v[148:151], v[190:193], v[116:119]
	v_mfma_f32_16x16x32_bf16 v[108:111], v[128:131], v[202:205], v[108:111]
	s_add_i32 m0, s51, 0xc000
	v_mfma_f32_16x16x32_bf16 v[100:103], v[148:151], v[202:205], v[100:103]
	v_mfma_f32_16x16x32_bf16 v[92:95], v[128:131], v[210:213], v[92:95]
	global_load_lds_dwordx4 v132, s[34:35]
	v_mfma_f32_16x16x32_bf16 v[84:87], v[148:151], v[210:213], v[84:87]
	v_mfma_f32_16x16x32_bf16 v[76:79], v[128:131], v[218:221], v[76:79]
	v_mfma_f32_16x16x32_bf16 v[68:71], v[148:151], v[218:221], v[68:71]
	v_mfma_f32_16x16x32_bf16 v[124:127], v[144:147], v[198:201], v[124:127]
	v_mfma_f32_16x16x32_bf16 v[116:119], v[152:155], v[198:201], v[116:119]
	v_mfma_f32_16x16x32_bf16 v[108:111], v[144:147], v[206:209], v[108:111]
	s_add_i32 m0, s51, 0xe000
	v_mfma_f32_16x16x32_bf16 v[100:103], v[152:155], v[206:209], v[100:103]
	v_mfma_f32_16x16x32_bf16 v[92:95], v[144:147], v[214:217], v[92:95]
	global_load_lds_dwordx4 v136, s[34:35]
	v_mfma_f32_16x16x32_bf16 v[84:87], v[152:155], v[214:217], v[84:87]
	v_mfma_f32_16x16x32_bf16 v[76:79], v[144:147], v[222:225], v[76:79]
	v_mfma_f32_16x16x32_bf16 v[68:71], v[152:155], v[222:225], v[68:71]
	s_setprio 0
	s_setprio 1
	v_mfma_f32_16x16x32_bf16 v[120:123], v[174:177], v[190:193], v[120:123]
	v_mfma_f32_16x16x32_bf16 v[112:115], v[182:185], v[190:193], v[112:115]
	v_mfma_f32_16x16x32_bf16 v[104:107], v[174:177], v[202:205], v[104:107]
	v_mfma_f32_16x16x32_bf16 v[96:99], v[182:185], v[202:205], v[96:99]
	v_mfma_f32_16x16x32_bf16 v[88:91], v[174:177], v[210:213], v[88:91]
	v_mfma_f32_16x16x32_bf16 v[80:83], v[182:185], v[210:213], v[80:83]
	v_mfma_f32_16x16x32_bf16 v[72:75], v[174:177], v[218:221], v[72:75]
	v_mfma_f32_16x16x32_bf16 v[64:67], v[182:185], v[218:221], v[64:67]
	v_mfma_f32_16x16x32_bf16 v[120:123], v[178:181], v[198:201], v[120:123]
	v_mfma_f32_16x16x32_bf16 v[112:115], v[186:189], v[198:201], v[112:115]
	v_mfma_f32_16x16x32_bf16 v[104:107], v[178:181], v[206:209], v[104:107]
	v_mfma_f32_16x16x32_bf16 v[96:99], v[186:189], v[206:209], v[96:99]
	v_mfma_f32_16x16x32_bf16 v[88:91], v[178:181], v[214:217], v[88:91]
	v_mfma_f32_16x16x32_bf16 v[80:83], v[186:189], v[214:217], v[80:83]
	v_mfma_f32_16x16x32_bf16 v[72:75], v[178:181], v[222:225], v[72:75]
	v_mfma_f32_16x16x32_bf16 v[64:67], v[186:189], v[222:225], v[64:67]
	s_setprio 0
	s_barrier
	s_add_i32 s62, s48, 0x10000
	s_mov_b32 m0, s62
	ds_read_b128 v[190:193], v173 offset:16384
	global_load_lds_dwordx4 v134, s[40:41]
	s_add_i32 m0, s62, 0x2000
	ds_read_b128 v[198:201], v244 offset:16384
	global_load_lds_dwordx4 v138, s[40:41]
	ds_read_b128 v[202:205], v173 offset:18432
	ds_read_b128 v[206:209], v244 offset:18432
	ds_read_b128 v[210:213], v173 offset:20480
	ds_read_b128 v[214:217], v244 offset:20480
	ds_read_b128 v[218:221], v173 offset:22528
	ds_read_b128 v[222:225], v244 offset:22528
	s_add_u32 s86, s40, 0x40000
	s_addc_u32 s87, s41, 0
	s_add_i32 s62, s48, 0x14000
	s_waitcnt vmcnt(4)
	s_waitcnt lgkmcnt(0)
	s_barrier
	s_setprio 1
	v_mfma_f32_16x16x32_bf16 v[60:63], v[128:131], v[190:193], v[60:63]
	v_mfma_f32_16x16x32_bf16 v[52:55], v[148:151], v[190:193], v[52:55]
	v_mfma_f32_16x16x32_bf16 v[44:47], v[128:131], v[202:205], v[44:47]
	s_mov_b32 m0, s62
	v_mfma_f32_16x16x32_bf16 v[36:39], v[148:151], v[202:205], v[36:39]
	v_mfma_f32_16x16x32_bf16 v[28:31], v[128:131], v[210:213], v[28:31]
	global_load_lds_dwordx4 v134, s[86:87]
	v_mfma_f32_16x16x32_bf16 v[20:23], v[148:151], v[210:213], v[20:23]
	v_mfma_f32_16x16x32_bf16 v[8:11], v[128:131], v[218:221], v[8:11]
	v_mfma_f32_16x16x32_bf16 v[4:7], v[148:151], v[218:221], v[4:7]
	v_mfma_f32_16x16x32_bf16 v[60:63], v[144:147], v[198:201], v[60:63]
	v_mfma_f32_16x16x32_bf16 v[52:55], v[152:155], v[198:201], v[52:55]
	v_mfma_f32_16x16x32_bf16 v[44:47], v[144:147], v[206:209], v[44:47]
	s_add_i32 m0, s62, 0x2000
	v_mfma_f32_16x16x32_bf16 v[36:39], v[152:155], v[206:209], v[36:39]
	v_mfma_f32_16x16x32_bf16 v[28:31], v[144:147], v[214:217], v[28:31]
	global_load_lds_dwordx4 v138, s[86:87]
	v_mfma_f32_16x16x32_bf16 v[20:23], v[152:155], v[214:217], v[20:23]
	v_mfma_f32_16x16x32_bf16 v[8:11], v[144:147], v[222:225], v[8:11]
	v_mfma_f32_16x16x32_bf16 v[4:7], v[152:155], v[222:225], v[4:7]
	s_setprio 0
	s_setprio 1
	v_mfma_f32_16x16x32_bf16 v[56:59], v[174:177], v[190:193], v[56:59]
	v_mfma_f32_16x16x32_bf16 v[48:51], v[182:185], v[190:193], v[48:51]
	v_mfma_f32_16x16x32_bf16 v[40:43], v[174:177], v[202:205], v[40:43]
	v_mfma_f32_16x16x32_bf16 v[32:35], v[182:185], v[202:205], v[32:35]
	v_mfma_f32_16x16x32_bf16 v[24:27], v[174:177], v[210:213], v[24:27]
	v_mfma_f32_16x16x32_bf16 v[16:19], v[182:185], v[210:213], v[16:19]
	v_mfma_f32_16x16x32_bf16 v[12:15], v[174:177], v[218:221], v[12:15]
	v_mfma_f32_16x16x32_bf16 v[0:3], v[182:185], v[218:221], v[0:3]
	v_mfma_f32_16x16x32_bf16 v[56:59], v[178:181], v[198:201], v[56:59]
	v_mfma_f32_16x16x32_bf16 v[48:51], v[186:189], v[198:201], v[48:51]
	v_mfma_f32_16x16x32_bf16 v[40:43], v[178:181], v[206:209], v[40:43]
	v_mfma_f32_16x16x32_bf16 v[32:35], v[186:189], v[206:209], v[32:35]
	v_mfma_f32_16x16x32_bf16 v[24:27], v[178:181], v[214:217], v[24:27]
	v_mfma_f32_16x16x32_bf16 v[16:19], v[186:189], v[214:217], v[16:19]
	v_mfma_f32_16x16x32_bf16 v[12:15], v[178:181], v[222:225], v[12:15]
	v_mfma_f32_16x16x32_bf16 v[0:3], v[186:189], v[222:225], v[0:3]
	s_setprio 0
	s_barrier
	s_mov_b32 m0, s51
	ds_read_b128 v[128:131], v248 offset:32768
	global_load_lds_dwordx4 v132, s[42:43]
	s_mov_b32 m0, s60
	ds_read_b128 v[144:147], v249 offset:32768
	global_load_lds_dwordx4 v136, s[42:43]
	ds_read_b128 v[148:151], v248 offset:34816
	ds_read_b128 v[152:155], v249 offset:34816
	ds_read_b128 v[174:177], v250 offset:32768
	ds_read_b128 v[178:181], v251 offset:32768
	ds_read_b128 v[182:185], v250 offset:34816
	ds_read_b128 v[186:189], v251 offset:34816
	ds_read_b128 v[190:193], v173 offset:32768
	ds_read_b128 v[198:201], v244 offset:32768
	ds_read_b128 v[202:205], v173 offset:34816
	ds_read_b128 v[206:209], v244 offset:34816
	ds_read_b128 v[210:213], v173 offset:36864
	ds_read_b128 v[214:217], v244 offset:36864
	ds_read_b128 v[218:221], v173 offset:38912
	ds_read_b128 v[222:225], v244 offset:38912
	s_add_u32 s42, s42, 0x40000
	s_addc_u32 s43, s43, 0
	s_waitcnt vmcnt(6)
	s_waitcnt lgkmcnt(0)
	s_barrier
	s_setprio 1
	v_mfma_f32_16x16x32_bf16 v[124:127], v[128:131], v[190:193], v[124:127]
	v_mfma_f32_16x16x32_bf16 v[116:119], v[148:151], v[190:193], v[116:119]
	v_mfma_f32_16x16x32_bf16 v[108:111], v[128:131], v[202:205], v[108:111]
	s_mov_b32 m0, s61
	v_mfma_f32_16x16x32_bf16 v[100:103], v[148:151], v[202:205], v[100:103]
	v_mfma_f32_16x16x32_bf16 v[92:95], v[128:131], v[210:213], v[92:95]
	global_load_lds_dwordx4 v132, s[42:43]
	v_mfma_f32_16x16x32_bf16 v[84:87], v[148:151], v[210:213], v[84:87]
	v_mfma_f32_16x16x32_bf16 v[76:79], v[128:131], v[218:221], v[76:79]
	v_mfma_f32_16x16x32_bf16 v[68:71], v[148:151], v[218:221], v[68:71]
	v_mfma_f32_16x16x32_bf16 v[124:127], v[144:147], v[198:201], v[124:127]
	v_mfma_f32_16x16x32_bf16 v[116:119], v[152:155], v[198:201], v[116:119]
	v_mfma_f32_16x16x32_bf16 v[108:111], v[144:147], v[206:209], v[108:111]
	s_mov_b32 m0, s64
	v_mfma_f32_16x16x32_bf16 v[100:103], v[152:155], v[206:209], v[100:103]
	v_mfma_f32_16x16x32_bf16 v[92:95], v[144:147], v[214:217], v[92:95]
	global_load_lds_dwordx4 v136, s[42:43]
	v_mfma_f32_16x16x32_bf16 v[84:87], v[152:155], v[214:217], v[84:87]
	v_mfma_f32_16x16x32_bf16 v[76:79], v[144:147], v[222:225], v[76:79]
	v_mfma_f32_16x16x32_bf16 v[68:71], v[152:155], v[222:225], v[68:71]
	s_setprio 0
	s_setprio 1
	v_mfma_f32_16x16x32_bf16 v[120:123], v[174:177], v[190:193], v[120:123]
	v_mfma_f32_16x16x32_bf16 v[112:115], v[182:185], v[190:193], v[112:115]
	v_mfma_f32_16x16x32_bf16 v[104:107], v[174:177], v[202:205], v[104:107]
	v_mfma_f32_16x16x32_bf16 v[96:99], v[182:185], v[202:205], v[96:99]
	v_mfma_f32_16x16x32_bf16 v[88:91], v[174:177], v[210:213], v[88:91]
	v_mfma_f32_16x16x32_bf16 v[80:83], v[182:185], v[210:213], v[80:83]
	v_mfma_f32_16x16x32_bf16 v[72:75], v[174:177], v[218:221], v[72:75]
	v_mfma_f32_16x16x32_bf16 v[64:67], v[182:185], v[218:221], v[64:67]
	v_mfma_f32_16x16x32_bf16 v[120:123], v[178:181], v[198:201], v[120:123]
	v_mfma_f32_16x16x32_bf16 v[112:115], v[186:189], v[198:201], v[112:115]
	v_mfma_f32_16x16x32_bf16 v[104:107], v[178:181], v[206:209], v[104:107]
	v_mfma_f32_16x16x32_bf16 v[96:99], v[186:189], v[206:209], v[96:99]
	v_mfma_f32_16x16x32_bf16 v[88:91], v[178:181], v[214:217], v[88:91]
	v_mfma_f32_16x16x32_bf16 v[80:83], v[186:189], v[214:217], v[80:83]
	v_mfma_f32_16x16x32_bf16 v[72:75], v[178:181], v[222:225], v[72:75]
	v_mfma_f32_16x16x32_bf16 v[64:67], v[186:189], v[222:225], v[64:67]
	s_setprio 0
	s_barrier
	s_add_i32 s42, s48, 0x18000
	s_add_u32 s40, s40, 0x80
	s_addc_u32 s41, s41, 0
	s_mov_b32 m0, s42
	ds_read_b128 v[190:193], v173 offset:49152
	global_load_lds_dwordx4 v134, s[40:41]
	s_add_i32 m0, s42, 0x2000
	ds_read_b128 v[198:201], v244 offset:49152
	global_load_lds_dwordx4 v138, s[40:41]
	ds_read_b128 v[202:205], v173 offset:51200
	ds_read_b128 v[206:209], v244 offset:51200
	ds_read_b128 v[210:213], v173 offset:53248
	ds_read_b128 v[214:217], v244 offset:53248
	ds_read_b128 v[218:221], v173 offset:55296
	ds_read_b128 v[222:225], v244 offset:55296
	s_add_u32 s40, s40, 0x40000
	s_addc_u32 s41, s41, 0
	s_add_i32 s42, s48, 0x1c000
	s_add_i32 s85, s85, 2
	s_add_u32 s34, s34, 0x100
	s_addc_u32 s35, s35, 0
	s_add_u32 s83, s83, 0x100
	s_addc_u32 s84, s84, 0
	s_waitcnt vmcnt(4)
	s_waitcnt lgkmcnt(0)
	s_barrier
	s_setprio 1
	v_mfma_f32_16x16x32_bf16 v[60:63], v[128:131], v[190:193], v[60:63]
	v_mfma_f32_16x16x32_bf16 v[52:55], v[148:151], v[190:193], v[52:55]
	v_mfma_f32_16x16x32_bf16 v[44:47], v[128:131], v[202:205], v[44:47]
	s_mov_b32 m0, s42
	v_mfma_f32_16x16x32_bf16 v[36:39], v[148:151], v[202:205], v[36:39]
	v_mfma_f32_16x16x32_bf16 v[28:31], v[128:131], v[210:213], v[28:31]
	global_load_lds_dwordx4 v134, s[40:41]
	v_mfma_f32_16x16x32_bf16 v[20:23], v[148:151], v[210:213], v[20:23]
	v_mfma_f32_16x16x32_bf16 v[8:11], v[128:131], v[218:221], v[8:11]
	v_mfma_f32_16x16x32_bf16 v[4:7], v[148:151], v[218:221], v[4:7]
	v_mfma_f32_16x16x32_bf16 v[60:63], v[144:147], v[198:201], v[60:63]
	v_mfma_f32_16x16x32_bf16 v[52:55], v[152:155], v[198:201], v[52:55]
	v_mfma_f32_16x16x32_bf16 v[44:47], v[144:147], v[206:209], v[44:47]
	s_add_i32 m0, s42, 0x2000
	v_mfma_f32_16x16x32_bf16 v[36:39], v[152:155], v[206:209], v[36:39]
	v_mfma_f32_16x16x32_bf16 v[28:31], v[144:147], v[214:217], v[28:31]
	global_load_lds_dwordx4 v138, s[40:41]
	v_mfma_f32_16x16x32_bf16 v[20:23], v[152:155], v[214:217], v[20:23]
	v_mfma_f32_16x16x32_bf16 v[8:11], v[144:147], v[222:225], v[8:11]
	v_mfma_f32_16x16x32_bf16 v[4:7], v[152:155], v[222:225], v[4:7]
	s_setprio 0
	s_setprio 1
	v_mfma_f32_16x16x32_bf16 v[56:59], v[174:177], v[190:193], v[56:59]
	v_mfma_f32_16x16x32_bf16 v[48:51], v[182:185], v[190:193], v[48:51]
	v_mfma_f32_16x16x32_bf16 v[40:43], v[174:177], v[202:205], v[40:43]
	v_mfma_f32_16x16x32_bf16 v[32:35], v[182:185], v[202:205], v[32:35]
	v_mfma_f32_16x16x32_bf16 v[24:27], v[174:177], v[210:213], v[24:27]
	v_mfma_f32_16x16x32_bf16 v[16:19], v[182:185], v[210:213], v[16:19]
	v_mfma_f32_16x16x32_bf16 v[12:15], v[174:177], v[218:221], v[12:15]
	v_mfma_f32_16x16x32_bf16 v[0:3], v[182:185], v[218:221], v[0:3]
	v_mfma_f32_16x16x32_bf16 v[56:59], v[178:181], v[198:201], v[56:59]
	v_mfma_f32_16x16x32_bf16 v[48:51], v[186:189], v[198:201], v[48:51]
	v_mfma_f32_16x16x32_bf16 v[40:43], v[178:181], v[206:209], v[40:43]
	v_mfma_f32_16x16x32_bf16 v[32:35], v[186:189], v[206:209], v[32:35]
	v_mfma_f32_16x16x32_bf16 v[24:27], v[178:181], v[214:217], v[24:27]
	v_mfma_f32_16x16x32_bf16 v[16:19], v[186:189], v[214:217], v[16:19]
	v_mfma_f32_16x16x32_bf16 v[12:15], v[178:181], v[222:225], v[12:15]
	v_mfma_f32_16x16x32_bf16 v[0:3], v[186:189], v[222:225], v[0:3]
	s_setprio 0
	s_barrier
	s_cmp_gt_u32 s85, 13
	s_cbranch_scc0 .LBB0_629
	s_and_b64 vcc, exec, s[2:3]
	s_cbranch_vccz .LBB0_632
	s_barrier
